# baseline (speedup 1.0000x reference)
; #define WAIT_V(n) asm volatile("s_waitcnt vmcnt(%0)" ::"n"(n) : "memory")
; template <int DQK, bool ALIBI>
; DEVI void attn_pass(const AttnArgs& a, f32x16 (&o)[4], const int tid_) {
;     ...
;   GLDS_KV(0, tile_of(0)); WAIT_V(0); __syncthreads();
;   for (int n = 0; n < cnt; ++n) {
;     const int buf = n & 1;
;     const int j = tile_of(n);
;     const bool last = (j == NT - 1);
;     if (n + 1 < cnt) GLDS_KV(buf ^ 1, tile_of(n + 1));
;     if (wactive) {
;       f32x16 p0 = f32x16{}, p1 = f32x16{};
;       const unsigned char* Ks = K_lds + buf * SHM_K + r32 * KPITCH;
;       const int key = KKEY(r32);
;     ...
;       if constexpr (DQK == 128 || DQK == 64 || DQK == 192) {
;         constexpr int NG4 = DQK / 64;
;         bf16x8 ka[4][2], kb[4][2];
; #pragma unroll
;         for (int s = 0; s < 4; ++s) { ka[s][0] = *(const bf16x8*)(Ks + KCB(s)); ka[s][1] = *(const bf16x8*)(Ks + 32 * KPITCH + KCB(s)); }
.LBB0_228:
	s_mov_b32 s12, s3
	s_and_b32 s34, s3, 1
	s_lshl_b32 s13, s34, 14
	v_add_u32_e32 v144, s13, v148
	v_add_u32_e32 v70, v144, v158
	v_add_u32_e32 v74, v144, v159
	ds_read_b128 v[66:69], v70 offset:32768
	ds_read_b128 v[70:73], v70 offset:40960
	ds_read_b128 v[160:163], v74 offset:32768
	ds_read_b128 v[164:167], v74 offset:40960
	v_add_u32_e32 v74, v144, v156
	ds_read_b128 v[184:187], v74 offset:32768
	ds_read_b128 v[188:191], v74 offset:40960
	v_add_u32_e32 v74, v144, v157
	ds_read_b128 v[192:195], v74 offset:32768
	ds_read_b128 v[196:199], v74 offset:40960
	s_add_i32 s3, s3, 1
	s_cmp_ge_u32 s12, s7
	s_cbranch_scc1 .LBB0_233
	s_cmp_gt_u32 s7, s3
	s_mov_b64 s[12:13], -1
	s_cbranch_scc1 .LBB0_231
	s_lshl_b32 s12, s34, 14
	s_xor_b32 s12, s12, 0x4000
	v_add_u32_e32 v200, s12, v150
	v_add_u32_e32 v201, 0x8000, v200
	s_nop 0
	v_readfirstlane_b32 s12, v201
	v_add_u32_e32 v201, 0xa000, v200
	s_mov_b32 m0, s12
	v_readfirstlane_b32 s12, v201
	global_load_lds_dwordx4 v[136:137], off
	s_mov_b32 m0, s12
	v_readfirstlane_b32 s12, v200
	v_add_u32_e32 v200, 0x2000, v200
	global_load_lds_dwordx4 v[138:139], off
	s_mov_b32 m0, s12
	v_readfirstlane_b32 s12, v200
	global_load_lds_dwordx4 v[140:141], off
	s_mov_b32 m0, s12
	s_mov_b64 s[12:13], 0
	global_load_lds_dwordx4 v[142:143], off

; #define SBAR() __builtin_amdgcn_sched_barrier(0)
; template <bool ALIBI, bool LAST>
; DEVI void softmax_tile(f32x16& p0, f32x16& p1, const float C, const float nslope2, const float dbase, float& m_reg, float& l_reg, float& alpha,
;                        bf16x8& pa0, bf16x8& pa1, bf16x8& pa2, bf16x8& pa3) {
;     ...
;   float pmax = p0[0];
; #pragma unroll
;   for (int r = 1; r < 16; ++r) pmax = fmaxf(pmax, p0[r]);
;   if constexpr (!LAST) {
; #pragma unroll
;     for (int r = 0; r < 16; ++r) pmax = fmaxf(pmax, p1[r]);
;   }
;   { auto rr = __builtin_amdgcn_permlane32_swap(__float_as_uint(pmax), __float_as_uint(pmax), false, false);
;     pmax = fmaxf(__uint_as_float(rr[0]), __uint_as_float(rr[1])); }
;   const float THRU = 8.f * LOG2E / C;
;   const float CU = C;
;   if (__builtin_expect(__all(pmax - m_reg <= THRU), 1)) { alpha = 1.f; }
;   else { float mn = fmaxf(m_reg, pmax); alpha = __builtin_amdgcn_exp2f((m_reg - mn) * CU); m_reg = mn; }
; template <int DQK, bool ALIBI>
; DEVI void attn_pass(const AttnArgs& a, f32x16 (&o)[4], const int tid_) {
;     ...
;     if (wactive) {
;       f32x16 p0 = f32x16{}, p1 = f32x16{};
;       const unsigned char* Ks = K_lds + buf * SHM_K + r32 * KPITCH;
;       const int key = KKEY(r32);
;     ...
;       if constexpr (DQK == 128 || DQK == 64 || DQK == 192) {
;         constexpr int NG4 = DQK / 64;
;         bf16x8 ka[4][2], kb[4][2];
; #pragma unroll
;         for (int s = 0; s < 4; ++s) { ka[s][0] = *(const bf16x8*)(Ks + KCB(s)); ka[s][1] = *(const bf16x8*)(Ks + 32 * KPITCH + KCB(s)); }
;         SBAR();
; #pragma unroll
;         for (int g = 0; g < NG4; ++g) {
;           if (g + 1 < NG4) {
; #pragma unroll
;             for (int s = 0; s < 4; ++s) { const int d1 = (g + 1) * 4 + s;
;               if (g & 1) { ka[s][0] = *(const bf16x8*)(Ks + KCB(d1)); ka[s][1] = *(const bf16x8*)(Ks + 32 * KPITCH + KCB(d1)); }
;               else       { kb[s][0] = *(const bf16x8*)(Ks + KCB(d1)); kb[s][1] = *(const bf16x8*)(Ks + 32 * KPITCH + KCB(d1)); } }
;           }
; #pragma unroll
;           for (int s = 0; s < 4; ++s) { const int d0 = g * 4 + s;
;             p0 = __builtin_amdgcn_mfma_f32_32x32x16_bf16((g & 1) ? kb[s][0] : ka[s][0], qr[d0], p0, 0, 0, 0);
;             p1 = __builtin_amdgcn_mfma_f32_32x32x16_bf16((g & 1) ? kb[s][1] : ka[s][1], qr[d0], p1, 0, 0, 0); }
;           SBAR();
.LBB0_233:
	s_and_saveexec_b64 s[12:13], s[4:5]
	s_cbranch_execz .LBB0_227
	s_lshl_b32 s34, s34, 14
	s_waitcnt lgkmcnt(6)
	v_mfma_f32_32x32x16_bf16 v[82:97], v[66:69], v[126:129], 0
	v_add_u32_e32 v168, v144, v153
	v_mfma_f32_32x32x16_bf16 v[66:81], v[70:73], v[126:129], 0
	s_waitcnt lgkmcnt(4)
	v_mfma_f32_32x32x16_bf16 v[82:97], v[160:163], v[122:125], v[82:97]
	v_mfma_f32_32x32x16_bf16 v[66:81], v[164:167], v[122:125], v[66:81]
	v_add_u32_e32 v164, v144, v155
	ds_read_b128 v[160:163], v164 offset:32768
	ds_read_b128 v[164:167], v164 offset:40960
	s_waitcnt lgkmcnt(4)
	v_mfma_f32_32x32x16_bf16 v[82:97], v[184:187], v[118:121], v[82:97]
	v_mfma_f32_32x32x16_bf16 v[66:81], v[188:191], v[118:121], v[66:81]
	ds_read_b128 v[184:187], v168 offset:32768
	ds_read_b128 v[188:191], v168 offset:40960
	v_add_u32_e32 v168, v144, v152
	v_add_u32_e32 v144, v144, v154
	s_waitcnt lgkmcnt(4)
	v_mfma_f32_32x32x16_bf16 v[82:97], v[192:195], v[114:117], v[82:97]
	ds_read_b128 v[192:195], v168 offset:32768
	ds_read_b128 v[200:203], v168 offset:40960
	ds_read_b128 v[204:207], v144 offset:32768
	ds_read_b128 v[208:211], v144 offset:40960
	v_mfma_f32_32x32x16_bf16 v[66:81], v[196:199], v[114:117], v[66:81]
	s_waitcnt lgkmcnt(6)
	v_mfma_f32_32x32x16_bf16 v[82:97], v[160:163], v[110:113], v[82:97]
	v_mfma_f32_32x32x16_bf16 v[66:81], v[164:167], v[110:113], v[66:81]
	s_waitcnt lgkmcnt(4)
	v_mfma_f32_32x32x16_bf16 v[82:97], v[184:187], v[106:109], v[82:97]
	v_mfma_f32_32x32x16_bf16 v[66:81], v[188:191], v[106:109], v[66:81]
	s_waitcnt lgkmcnt(2)
	v_mfma_f32_32x32x16_bf16 v[82:97], v[192:195], v[102:105], v[82:97]
	v_mfma_f32_32x32x16_bf16 v[66:81], v[200:203], v[102:105], v[66:81]
	s_waitcnt lgkmcnt(0)
	v_mfma_f32_32x32x16_bf16 v[82:97], v[204:207], v[98:101], v[82:97]
	v_mfma_f32_32x32x16_bf16 v[66:81], v[208:211], v[98:101], v[66:81]
	v_add_u32_e32 v211, s34, v145
	ds_read_b64_tr_b16 v[192:193], v211 offset:0x0
	ds_read_b64_tr_b16 v[194:195], v211 offset:0x800
	ds_read_b64_tr_b16 v[196:197], v211 offset:0x200
	ds_read_b64_tr_b16 v[198:199], v211 offset:0xa00
	ds_read_b64_tr_b16 v[200:201], v211 offset:0x400
	ds_read_b64_tr_b16 v[202:203], v211 offset:0xc00
	ds_read_b64_tr_b16 v[204:205], v211 offset:0x600
	ds_read_b64_tr_b16 v[206:207], v211 offset:0xe00
	s_nop 1
	v_max3_f32 v144, v82, v83, v84
	v_max3_f32 v144, v144, v85, v86
	v_max3_f32 v144, v144, v87, v88
	v_max3_f32 v144, v144, v89, v90
	v_max3_f32 v144, v144, v91, v92
	v_max3_f32 v144, v144, v93, v94
	v_max3_f32 v144, v144, v95, v96
	v_max3_f32 v144, v144, v97, v66
	v_max3_f32 v144, v144, v67, v68
	v_max3_f32 v144, v144, v69, v70
	v_max3_f32 v144, v144, v71, v72
	v_max3_f32 v144, v144, v73, v74
	v_max3_f32 v144, v144, v75, v76
	v_max3_f32 v144, v144, v77, v78
	v_max3_f32 v144, v144, v79, v80
	v_max_f32_e32 v144, v144, v81
	v_mov_b32_e32 v160, v144
	s_nop 1
	v_permlane32_swap_b32_e32 v144, v160
	v_max_f32_e32 v144, v144, v160
	v_sub_f32_e32 v160, v144, v151
	v_cmp_ge_f32_e32 vcc, s18, v160
	s_cmp_eq_u64 vcc, exec
	s_cbranch_scc0 .Lmy_A_slow
	v_mov_b32_e32 v144, 1.0
